# P3 cmp_task: the 79 packed fp32 add/mul between the MFMAs split into scalar ops (doc 7.5); bit-identical
# baseline (speedup 1.0000x reference)
; #define MFMA32(a, b, c) __builtin_amdgcn_mfma_f32_32x32x16_bf16((a), (b), (c), 0, 0, 0)
; DI int crow(int r, int h) { return (r & 3) + 8 * (r >> 2) + 4 * h; }
; DI void cmp_task(const bf16_t* Z, const bf16_t* KCC, const bf16_t* VCT, bf16_t* OCMP, unsigned* selm, int b, int hk, int tg, int lane) {
;     const int r32 = lane & 31, h = lane >> 5;
;     const int tok = 8 * tg + (r32 >> 2), g = r32 & 3, head = hk * 4 + g;
;     const size_t grow = (size_t)b * SEQ + tok;
;     const bf16_t* zr = Z + grow * NZ;
;     bf16x8 qf[4];
; #pragma unroll
;     for (int s = 0; s < 4; ++s) qf[s] = *(const bf16x8*)(zr + ZC_QA + head * 64 + 16 * s + 8 * h);
;     const bf16_t* kc = KCC + (size_t)(b * 2 + hk) * 128 * 64; const bf16_t* vt = VCT + (size_t)(b * 2 + hk) * 64 * 128;
;     const int tmax = 8 * tg + 7;
;     const int nsub = tmax < 31 ? 0 : (((tmax - 31) >> 4) >> 5) + 1;
;     f32x16 p[4];
; #pragma unroll
;     for (int sub = 0; sub < 4; ++sub) {
;         if (sub < nsub) {
;             p[sub] = f16zero();
; #pragma unroll
;             for (int s = 0; s < 4; ++s) { const bf16x8 af = *(const bf16x8*)(kc + (size_t)(32 * sub + r32) * 64 + 16 * s + 8 * h); p[sub] = MFMA32(af, qf[s], p[sub]); }
; #pragma unroll
;             for (int r = 0; r < 16; ++r) { const int n = 32 * sub + crow(r, h); p[sub][r] = (16 * n + 31 <= tok) ? p[sub][r] * SM_C : NINF; }
.Lcmp_have:
	s_and_b32 s9, s8, 7
	s_lshr_b32 s8, s8, 3
	s_lshr_b32 s10, s92, 6
	s_add_i32 s8, s8, s10
	s_sub_i32 s8, 3, s8
	s_and_b32 s8, s8, 3
	s_lshl_b32 s8, s8, 11
	s_add_i32 s9, s9, s8
	s_and_b32 s8, s92, -8
	s_add_i32 s9, s9, s8
	s_lshr_b32 s10, s9, 5
	s_and_b32 s10, s10, 0xc0
	s_add_i32 s10, s10, s9
	s_ashr_i32 s8, s9, 9
	s_and_b32 s54, s10, 0xff
	s_bfe_u32 s14, s9, 0x10008
	s_lshl_b32 s50, s54, 3
	s_ashr_i32 s9, s8, 31
	v_or_b32_e32 v131, s50, v113
	s_lshl_b64 s[10:11], s[8:9], 11
	v_or_b32_e32 v122, s10, v131
	v_mov_b64_e32 v[2:3], s[22:23]
	s_movk_i32 s9, 0x2200
	v_mad_u64_u32 v[2:3], s[48:49], v122, s9, v[2:3]
	v_lshl_or_b32 v1, s14, 8, v115
	v_mad_i32_i24 v3, s11, v244, v3
	v_lshlrev_b32_e32 v42, 1, v1
	v_lshl_add_u64 v[2:3], v[2:3], 0, v[42:43]
	v_mov_b32_e32 v41, v43
	v_lshl_add_u64 v[2:3], v[2:3], 0, v[40:41]
	global_load_dwordx4 v[30:33], v[2:3], off
	global_load_dwordx4 v[26:29], v[2:3], off offset:32
	global_load_dwordx4 v[22:25], v[2:3], off offset:64
	global_load_dwordx4 v[18:21], v[2:3], off offset:96
	s_lshl_b32 s8, s8, 1
	s_or_b32 s8, s8, s14
	s_ashr_i32 s9, s8, 31
	s_lshl_b64 s[8:9], s[8:9], 14
	s_or_b32 s10, s50, 7
	s_cmp_lt_u32 s10, 31
	s_cselect_b64 s[48:49], -1, 0
	s_cmp_gt_u32 s10, 30
	v_mov_b32_e32 v123, s11
	s_cselect_b64 s[10:11], -1, 0
	v_lshl_add_u64 v[124:125], v[44:45], 0, s[8:9]
	v_readfirstlane_b32 s99, v0
	s_lshr_b32 s99, s99, 6
	s_lshl_b32 s99, s99, 14
	v_readfirstlane_b32 s78, v78
	v_readfirstlane_b32 s79, v79
	s_add_u32 s78, s78, s8
	s_addc_u32 s79, s79, s9
	v_mbcnt_lo_u32_b32 v34, -1, 0
	v_mbcnt_hi_u32_b32 v34, -1, v34
	v_lshrrev_b32_e32 v35, 5, v34
	v_and_b32_e32 v34, 31, v34
	v_lshlrev_b32_e32 v34, 8, v34
	v_lshl_or_b32 v34, v35, 4, v34
	s_add_i32 m0, s99, 0x0
	s_add_u32 s80, s78, 0x0
	s_addc_u32 s81, s79, 0
	global_load_lds_dwordx4 v34, s[80:81]
	s_add_i32 m0, s99, 0x400
	s_add_u32 s80, s78, 0x20
	s_addc_u32 s81, s79, 0
	global_load_lds_dwordx4 v34, s[80:81]
	s_add_i32 m0, s99, 0x800
	s_add_u32 s80, s78, 0x40
	s_addc_u32 s81, s79, 0
	global_load_lds_dwordx4 v34, s[80:81]
	s_add_i32 m0, s99, 0xc00
	s_add_u32 s80, s78, 0x60
	s_addc_u32 s81, s79, 0
	global_load_lds_dwordx4 v34, s[80:81]
	s_add_i32 m0, s99, 0x1000
	s_add_u32 s80, s78, 0x80
	s_addc_u32 s81, s79, 0
	global_load_lds_dwordx4 v34, s[80:81]
	s_add_i32 m0, s99, 0x1400
	s_add_u32 s80, s78, 0xa0
	s_addc_u32 s81, s79, 0
	global_load_lds_dwordx4 v34, s[80:81]
	s_add_i32 m0, s99, 0x1800
	s_add_u32 s80, s78, 0xc0
	s_addc_u32 s81, s79, 0
	global_load_lds_dwordx4 v34, s[80:81]
	s_add_i32 m0, s99, 0x1c00
	s_add_u32 s80, s78, 0xe0
	s_addc_u32 s81, s79, 0
	global_load_lds_dwordx4 v34, s[80:81]
	s_add_i32 m0, s99, 0x2000
	s_add_u32 s80, s78, 0x2000
	s_addc_u32 s81, s79, 0
	global_load_lds_dwordx4 v34, s[80:81]
	s_add_i32 m0, s99, 0x2400
	s_add_u32 s80, s78, 0x2020
	s_addc_u32 s81, s79, 0
	global_load_lds_dwordx4 v34, s[80:81]
	s_add_i32 m0, s99, 0x2800
	s_add_u32 s80, s78, 0x2040
	s_addc_u32 s81, s79, 0
	global_load_lds_dwordx4 v34, s[80:81]
	s_add_i32 m0, s99, 0x2c00
	s_add_u32 s80, s78, 0x2060
	s_addc_u32 s81, s79, 0
	global_load_lds_dwordx4 v34, s[80:81]
	s_add_i32 m0, s99, 0x3000
	s_add_u32 s80, s78, 0x2080
	s_addc_u32 s81, s79, 0
	global_load_lds_dwordx4 v34, s[80:81]
	s_add_i32 m0, s99, 0x3400
	s_add_u32 s80, s78, 0x20a0
	s_addc_u32 s81, s79, 0
	global_load_lds_dwordx4 v34, s[80:81]
	s_add_i32 m0, s99, 0x3800
	s_add_u32 s80, s78, 0x20c0
	s_addc_u32 s81, s79, 0
	global_load_lds_dwordx4 v34, s[80:81]
	s_add_i32 m0, s99, 0x3c00
	s_add_u32 s80, s78, 0x20e0
	s_addc_u32 s81, s79, 0
	global_load_lds_dwordx4 v34, s[80:81]
	v_mov_b32_e32 v121, 0xff800000
	s_and_b64 vcc, exec, s[48:49]
	v_lshlrev_b32_e32 v126, 1, v38
	v_mov_b32_e32 v128, 0xff800000
	v_mov_b32_e32 v129, 0xff800000
	v_mov_b32_e32 v130, 0xff800000
	v_mov_b32_e32 v134, 0xff800000
	v_mov_b32_e32 v135, 0xff800000
	v_mov_b32_e32 v139, 0xff800000
	v_mov_b32_e32 v140, 0xff800000
	v_mov_b32_e32 v141, 0xff800000
	v_mov_b32_e32 v142, 0xff800000
	v_mov_b32_e32 v143, 0xff800000
	v_mov_b32_e32 v144, 0xff800000
	v_mov_b32_e32 v145, 0xff800000
	v_mov_b32_e32 v146, 0xff800000
	v_mov_b32_e32 v147, 0xff800000
	v_mov_b32_e32 v148, 0xff800000
	v_mov_b32_e32 v149, 0xff800000
	s_cbranch_vccnz .LBB0_483
	v_mov_b32_e32 v127, v43
	v_lshl_add_u64 v[94:95], v[124:125], 0, v[126:127]
	global_load_dwordx4 v[2:5], v[94:95], off
	global_load_dwordx4 v[140:143], v[94:95], off offset:32
	global_load_dwordx4 v[150:153], v[94:95], off offset:64
	global_load_dwordx4 v[154:157], v[94:95], off offset:96
	v_cmp_le_u32_e32 vcc, v46, v131
	s_waitcnt vmcnt(3)
	v_mfma_f32_32x32x16_bf16 v[2:17], v[2:5], v[30:33], 0
	s_waitcnt vmcnt(2)
	v_mfma_f32_32x32x16_bf16 v[2:17], v[140:143], v[26:29], v[2:17]
	s_waitcnt vmcnt(1)
	v_mfma_f32_32x32x16_bf16 v[2:17], v[150:153], v[22:25], v[2:17]
	s_waitcnt vmcnt(0)
	v_mfma_f32_32x32x16_bf16 v[2:17], v[154:157], v[18:21], v[2:17]
	s_nop 11
	v_mul_f32_e32 v2, s46, v2
	v_mul_f32_e32 v3, s46, v3
	s_nop 0
	v_cndmask_b32_e32 v128, v245, v2, vcc
	v_cmp_le_u32_e32 vcc, v37, v131
	v_mul_f32_e32 v1, 0x3e38aa3b, v4
	s_nop 0
	v_cndmask_b32_e32 v129, v245, v3, vcc
	v_cmp_le_u32_e32 vcc, v117, v131
	v_mul_f32_e32 v2, s46, v6
	v_mul_f32_e32 v3, s46, v7
	s_nop 0
	v_cndmask_b32_e32 v130, v245, v1, vcc
	v_mul_f32_e32 v1, 0x3e38aa3b, v5
	v_cmp_le_u32_e32 vcc, v119, v131
	s_nop 1
	v_cndmask_b32_e32 v134, v245, v1, vcc
	v_cmp_le_u32_e32 vcc, v48, v131
	v_mul_f32_e32 v1, 0x3e38aa3b, v8
	s_nop 0
	v_cndmask_b32_e32 v135, v245, v2, vcc
	v_cmp_le_u32_e32 vcc, v39, v131
	s_nop 1
	v_cndmask_b32_e32 v139, v245, v3, vcc
	v_cmp_le_u32_e32 vcc, v202, v131
	v_mul_f32_e32 v2, s46, v10
	v_mul_f32_e32 v3, s46, v11
	s_nop 0
	v_cndmask_b32_e32 v140, v245, v1, vcc
	v_mul_f32_e32 v1, 0x3e38aa3b, v9
	v_cmp_le_u32_e32 vcc, v203, v131
	s_nop 1
	v_cndmask_b32_e32 v141, v245, v1, vcc
	v_cmp_le_u32_e32 vcc, v50, v131
	v_mul_f32_e32 v1, 0x3e38aa3b, v12
	s_nop 0
	v_cndmask_b32_e32 v142, v245, v2, vcc
	v_cmp_le_u32_e32 vcc, v47, v131
	s_nop 1
	v_cndmask_b32_e32 v143, v245, v3, vcc
	v_cmp_le_u32_e32 vcc, v204, v131
	v_mul_f32_e32 v2, s46, v14
	v_mul_f32_e32 v3, s46, v15
	s_nop 0
	v_cndmask_b32_e32 v144, v245, v1, vcc
	v_mul_f32_e32 v1, 0x3e38aa3b, v13
	v_cmp_le_u32_e32 vcc, v205, v131
	s_nop 1
	v_cndmask_b32_e32 v145, v245, v1, vcc
	v_cmp_le_u32_e32 vcc, v52, v131
	v_mul_f32_e32 v1, 0x3e38aa3b, v16
	s_nop 0
	v_cndmask_b32_e32 v146, v245, v2, vcc
	v_cmp_le_u32_e32 vcc, v49, v131
	s_nop 1
	v_cndmask_b32_e32 v147, v245, v3, vcc
	v_cmp_le_u32_e32 vcc, v206, v131
	s_nop 1
	v_cndmask_b32_e32 v148, v245, v1, vcc
	v_mul_f32_e32 v1, 0x3e38aa3b, v17
	v_cmp_le_u32_e32 vcc, v207, v131
	s_nop 1
	v_cndmask_b32_e32 v149, v245, v1, vcc
; #define MFMA32(a, b, c) __builtin_amdgcn_mfma_f32_32x32x16_bf16((a), (b), (c), 0, 0, 0)
; DI int crow(int r, int h) { return (r & 3) + 8 * (r >> 2) + 4 * h; }
; DI void cmp_task(const bf16_t* Z, const bf16_t* KCC, const bf16_t* VCT, bf16_t* OCMP, unsigned* selm, int b, int hk, int tg, int lane) {
;     ...
;     for (int sub = 0; sub < 4; ++sub) {
;         if (sub < nsub) {
;             p[sub] = f16zero();
; #pragma unroll
;             for (int s = 0; s < 4; ++s) { const bf16x8 af = *(const bf16x8*)(kc + (size_t)(32 * sub + r32) * 64 + 16 * s + 8 * h); p[sub] = MFMA32(af, qf[s], p[sub]); }
; #pragma unroll
;             for (int r = 0; r < 16; ++r) { const int n = 32 * sub + crow(r, h); p[sub][r] = (16 * n + 31 <= tok) ? p[sub][r] * SM_C : NINF; }
.LBB0_483:
	s_sub_i32 s50, s50, 24
	s_lshr_b32 s50, s50, 9
	s_add_i32 s50, s50, 1
	s_and_b64 s[48:49], exec, s[48:49]
	s_cselect_b32 s55, 0, s50
	s_cmp_gt_u32 s55, 1
	s_cselect_b64 s[48:49], -1, 0
	s_cmp_lt_u32 s55, 2
	v_mov_b32_e32 v150, 0xff800000
	v_mov_b32_e32 v151, 0xff800000
	v_mov_b32_e32 v152, 0xff800000
	v_mov_b32_e32 v153, 0xff800000
	v_mov_b32_e32 v154, 0xff800000
	v_mov_b32_e32 v155, 0xff800000
	v_mov_b32_e32 v156, 0xff800000
	v_mov_b32_e32 v157, 0xff800000
	v_mov_b32_e32 v158, 0xff800000
	v_mov_b32_e32 v159, 0xff800000
	v_mov_b32_e32 v160, 0xff800000
	v_mov_b32_e32 v161, 0xff800000
	v_mov_b32_e32 v162, 0xff800000
	v_mov_b32_e32 v163, 0xff800000
	v_mov_b32_e32 v164, 0xff800000
	s_cbranch_scc1 .LBB0_485
	v_mov_b32_e32 v127, v43
	v_lshl_add_u64 v[2:3], v[124:125], 0, v[126:127]
	v_add_co_u32_e32 v94, vcc, 0x1000, v2
	s_nop 1
	v_addc_co_u32_e32 v95, vcc, 0, v3, vcc
	global_load_dwordx4 v[2:5], v[94:95], off
	global_load_dwordx4 v[150:153], v[94:95], off offset:32
	global_load_dwordx4 v[154:157], v[94:95], off offset:64
	global_load_dwordx4 v[158:161], v[94:95], off offset:96
	v_cmp_le_u32_e32 vcc, v54, v131
	s_waitcnt vmcnt(3)
	v_mfma_f32_32x32x16_bf16 v[2:17], v[2:5], v[30:33], 0
	s_waitcnt vmcnt(2)
	v_mfma_f32_32x32x16_bf16 v[2:17], v[150:153], v[26:29], v[2:17]
	s_waitcnt vmcnt(1)
	v_mfma_f32_32x32x16_bf16 v[2:17], v[154:157], v[22:25], v[2:17]
	s_waitcnt vmcnt(0)
	v_mfma_f32_32x32x16_bf16 v[2:17], v[158:161], v[18:21], v[2:17]
	s_nop 11
	v_mul_f32_e32 v2, s46, v2
	v_mul_f32_e32 v3, s46, v3
	s_nop 0
	v_cndmask_b32_e32 v121, v245, v2, vcc
	v_cmp_le_u32_e32 vcc, v51, v131
	v_mul_f32_e32 v1, 0x3e38aa3b, v4
	s_nop 0
	v_cndmask_b32_e32 v150, v245, v3, vcc
	v_cmp_le_u32_e32 vcc, v208, v131
	v_mul_f32_e32 v2, s46, v6
	v_mul_f32_e32 v3, s46, v7
	s_nop 0
	v_cndmask_b32_e32 v151, v245, v1, vcc
	v_mul_f32_e32 v1, 0x3e38aa3b, v5
	v_cmp_le_u32_e32 vcc, v209, v131
	s_nop 1
	v_cndmask_b32_e32 v152, v245, v1, vcc
	v_cmp_le_u32_e32 vcc, v56, v131
	v_mul_f32_e32 v1, 0x3e38aa3b, v8
	s_nop 0
	v_cndmask_b32_e32 v153, v245, v2, vcc
	v_cmp_le_u32_e32 vcc, v53, v131
	s_nop 1
	v_cndmask_b32_e32 v154, v245, v3, vcc
	v_cmp_le_u32_e32 vcc, v210, v131
	v_mul_f32_e32 v2, s46, v10
	v_mul_f32_e32 v3, s46, v11
	s_nop 0
	v_cndmask_b32_e32 v155, v245, v1, vcc
	v_mul_f32_e32 v1, 0x3e38aa3b, v9
	v_cmp_le_u32_e32 vcc, v211, v131
	s_nop 1
	v_cndmask_b32_e32 v156, v245, v1, vcc
	v_cmp_le_u32_e32 vcc, v58, v131
	v_mul_f32_e32 v1, 0x3e38aa3b, v12
	s_nop 0
	v_cndmask_b32_e32 v157, v245, v2, vcc
	v_cmp_le_u32_e32 vcc, v55, v131
	s_nop 1
	v_cndmask_b32_e32 v158, v245, v3, vcc
	v_cmp_le_u32_e32 vcc, v212, v131
	v_mul_f32_e32 v2, s46, v14
	v_mul_f32_e32 v3, s46, v15
	s_nop 0
	v_cndmask_b32_e32 v159, v245, v1, vcc
	v_mul_f32_e32 v1, 0x3e38aa3b, v13
	v_cmp_le_u32_e32 vcc, v213, v131
	s_nop 1
	v_cndmask_b32_e32 v160, v245, v1, vcc
	v_cmp_le_u32_e32 vcc, v60, v131
	v_mul_f32_e32 v1, 0x3e38aa3b, v16
	s_nop 0
	v_cndmask_b32_e32 v161, v245, v2, vcc
	v_cmp_le_u32_e32 vcc, v57, v131
	s_nop 1
	v_cndmask_b32_e32 v162, v245, v3, vcc
	v_cmp_le_u32_e32 vcc, v216, v131
	s_nop 1
	v_cndmask_b32_e32 v163, v245, v1, vcc
	v_mul_f32_e32 v1, 0x3e38aa3b, v17
	v_cmp_le_u32_e32 vcc, v217, v131
	s_nop 1
	v_cndmask_b32_e32 v164, v245, v1, vcc
.LBB0_485:
	s_cmp_gt_u32 s55, 2
	v_mov_b32_e32 v165, 0xff800000
	s_cselect_b64 s[50:51], -1, 0
	s_cmp_lt_u32 s55, 3
	v_mov_b32_e32 v166, 0xff800000
	v_mov_b32_e32 v167, 0xff800000
	v_mov_b32_e32 v174, 0xff800000
	v_mov_b32_e32 v175, 0xff800000
	v_mov_b32_e32 v190, 0xff800000
	v_mov_b32_e32 v191, 0xff800000
	v_mov_b32_e32 v192, 0xff800000
	v_mov_b32_e32 v193, 0xff800000
	v_mov_b32_e32 v194, 0xff800000
	v_mov_b32_e32 v195, 0xff800000
	v_mov_b32_e32 v196, 0xff800000
	v_mov_b32_e32 v197, 0xff800000
	v_mov_b32_e32 v247, 0xff800000
	v_mov_b32_e32 v248, 0xff800000
	v_mov_b32_e32 v249, 0xff800000
	v_mov_b32_e32 v250, 0xff800000
	s_cbranch_scc1 .LBB0_487
	v_mov_b32_e32 v127, v43
	v_lshl_add_u64 v[2:3], v[124:125], 0, v[126:127]
	v_add_co_u32_e32 v94, vcc, 0x2000, v2
	s_nop 1
	v_addc_co_u32_e32 v95, vcc, 0, v3, vcc
	global_load_dwordx4 v[2:5], v[94:95], off
	global_load_dwordx4 v[166:169], v[94:95], off offset:32
	global_load_dwordx4 v[170:173], v[94:95], off offset:64
	global_load_dwordx4 v[176:179], v[94:95], off offset:96
	v_cmp_le_u32_e32 vcc, v62, v131
	s_waitcnt vmcnt(3)
	v_mfma_f32_32x32x16_bf16 v[2:17], v[2:5], v[30:33], 0
	s_waitcnt vmcnt(2)
	v_mfma_f32_32x32x16_bf16 v[2:17], v[166:169], v[26:29], v[2:17]
	s_waitcnt vmcnt(1)
	v_mfma_f32_32x32x16_bf16 v[2:17], v[170:173], v[22:25], v[2:17]
	s_waitcnt vmcnt(0)
	v_mfma_f32_32x32x16_bf16 v[2:17], v[176:179], v[18:21], v[2:17]
	s_nop 11
	v_mul_f32_e32 v2, s46, v2
	v_mul_f32_e32 v3, s46, v3
	s_nop 0
	v_cndmask_b32_e32 v166, v245, v2, vcc
	v_cmp_le_u32_e32 vcc, v59, v131
	v_mul_f32_e32 v1, 0x3e38aa3b, v4
	s_nop 0
	v_cndmask_b32_e32 v167, v245, v3, vcc
	v_cmp_le_u32_e32 vcc, v218, v131
	v_mul_f32_e32 v2, s46, v6
	v_mul_f32_e32 v3, s46, v7
	s_nop 0
	v_cndmask_b32_e32 v174, v245, v1, vcc
	v_mul_f32_e32 v1, 0x3e38aa3b, v5
	v_cmp_le_u32_e32 vcc, v219, v131
	s_nop 1
	v_cndmask_b32_e32 v175, v245, v1, vcc
	v_cmp_le_u32_e32 vcc, v64, v131
	v_mul_f32_e32 v1, 0x3e38aa3b, v8
	s_nop 0
	v_cndmask_b32_e32 v190, v245, v2, vcc
	v_cmp_le_u32_e32 vcc, v61, v131
	s_nop 1
	v_cndmask_b32_e32 v191, v245, v3, vcc
	v_cmp_le_u32_e32 vcc, v220, v131
	v_mul_f32_e32 v2, s46, v10
	v_mul_f32_e32 v3, s46, v11
	s_nop 0
	v_cndmask_b32_e32 v192, v245, v1, vcc
	v_mul_f32_e32 v1, 0x3e38aa3b, v9
	v_cmp_le_u32_e32 vcc, v221, v131
	s_nop 1
	v_cndmask_b32_e32 v193, v245, v1, vcc
	v_cmp_le_u32_e32 vcc, v66, v131
	v_mul_f32_e32 v1, 0x3e38aa3b, v12
	s_nop 0
	v_cndmask_b32_e32 v194, v245, v2, vcc
	v_cmp_le_u32_e32 vcc, v63, v131
	s_nop 1
	v_cndmask_b32_e32 v195, v245, v3, vcc
	v_cmp_le_u32_e32 vcc, v222, v131
	v_mul_f32_e32 v2, s46, v14
	v_mul_f32_e32 v3, s46, v15
	s_nop 0
	v_cndmask_b32_e32 v196, v245, v1, vcc
	v_mul_f32_e32 v1, 0x3e38aa3b, v13
	v_cmp_le_u32_e32 vcc, v223, v131
	s_nop 1
	v_cndmask_b32_e32 v197, v245, v1, vcc
	v_cmp_le_u32_e32 vcc, v68, v131
	v_mul_f32_e32 v1, 0x3e38aa3b, v16
	s_nop 0
	v_cndmask_b32_e32 v247, v245, v2, vcc
	v_cmp_le_u32_e32 vcc, v65, v131
	s_nop 1
	v_cndmask_b32_e32 v248, v245, v3, vcc
	v_cmp_le_u32_e32 vcc, v224, v131
	s_nop 1
	v_cndmask_b32_e32 v249, v245, v1, vcc
	v_mul_f32_e32 v1, 0x3e38aa3b, v17
	v_cmp_le_u32_e32 vcc, v225, v131
	s_nop 1
	v_cndmask_b32_e32 v250, v245, v1, vcc
; DI int crow(int r, int h) { return (r & 3) + 8 * (r >> 2) + 4 * h; }
; DI float fexp2(float x) { return __builtin_amdgcn_exp2f(x); }
; DI void cmp_task(const bf16_t* Z, const bf16_t* KCC, const bf16_t* VCT, bf16_t* OCMP, unsigned* selm, int b, int hk, int tg, int lane) {
;     ...
;             for (int r = 0; r < 16; ++r) { const int n = 32 * sub + crow(r, h); p[sub][r] = (16 * n + 31 <= tok) ? p[sub][r] * SM_C : NINF; }
;         } else {
; #pragma unroll
;             for (int r = 0; r < 16; ++r) p[sub][r] = NINF;
;         }
;     }
;     float mx = NINF;
; #pragma unroll
;     for (int sub = 0; sub < 4; ++sub)
; #pragma unroll
;         for (int r = 0; r < 16; ++r) mx = fmaxf(mx, p[sub][r]);
;     mx = fmaxf(mx, __shfl_xor(mx, 32));
;     const float mu = (mx == NINF) ? 0.f : mx;
;     float sum = 0.f;
; #pragma unroll
;     for (int sub = 0; sub < 4; ++sub)
; #pragma unroll
;         for (int r = 0; r < 16; ++r) { p[sub][r] = fexp2(p[sub][r] - mu); sum += p[sub][r]; }
;     const float lt = sum + __shfl_xor(sum, 32); const float inv = lt > 0.f ? 1.0f / lt : 0.f;
.LBB0_487:
	s_cmp_gt_u32 s55, 3
	s_cselect_b64 s[52:53], -1, 0
	s_cmp_lt_u32 s55, 4
	v_mov_b32_e32 v127, 0xff800000
	v_mov_b32_e32 v251, 0xff800000
	v_mov_b32_e32 v252, 0xff800000
	v_mov_b32_e32 v215, 0xff800000
	v_mov_b32_e32 v34, 0xff800000
	v_mov_b32_e32 v137, 0xff800000
	v_mov_b32_e32 v1, 0xff800000
	v_mov_b32_e32 v234, 0xff800000
	v_mov_b32_e32 v75, 0xff800000
	v_mov_b32_e32 v82, 0xff800000
	v_mov_b32_e32 v77, 0xff800000
	v_mov_b32_e32 v14, 0xff800000
	v_mov_b32_e32 v15, 0xff800000
	v_mov_b32_e32 v16, 0xff800000
	v_mov_b32_e32 v17, 0xff800000
	s_cbranch_scc1 .LBB0_489
	v_mov_b32_e32 v127, v43
	v_lshl_add_u64 v[2:3], v[124:125], 0, v[126:127]
	v_add_co_u32_e32 v94, vcc, 0x3000, v2
	s_nop 1
	v_addc_co_u32_e32 v95, vcc, 0, v3, vcc
	global_load_dwordx4 v[2:5], v[94:95], off
	global_load_dwordx4 v[168:171], v[94:95], off offset:32
	global_load_dwordx4 v[176:179], v[94:95], off offset:64
	global_load_dwordx4 v[180:183], v[94:95], off offset:96
	v_cmp_le_u32_e32 vcc, v70, v131
	s_waitcnt vmcnt(3)
	v_mfma_f32_32x32x16_bf16 v[2:17], v[2:5], v[30:33], 0
	s_waitcnt vmcnt(2)
	v_mfma_f32_32x32x16_bf16 v[2:17], v[168:171], v[26:29], v[2:17]
	s_waitcnt vmcnt(1)
	v_mfma_f32_32x32x16_bf16 v[2:17], v[176:179], v[22:25], v[2:17]
	s_waitcnt vmcnt(0)
	v_mfma_f32_32x32x16_bf16 v[2:17], v[180:183], v[18:21], v[2:17]
	s_nop 11
	v_mul_f32_e32 v2, s46, v2
	v_mul_f32_e32 v3, s46, v3
	s_nop 0
	v_cndmask_b32_e32 v165, v245, v2, vcc
	v_cmp_le_u32_e32 vcc, v67, v131
	v_mul_f32_e32 v1, 0x3e38aa3b, v4
	s_nop 0
	v_cndmask_b32_e32 v127, v245, v3, vcc
	v_cmp_le_u32_e32 vcc, v226, v131
	v_mul_f32_e32 v2, s46, v6
	v_mul_f32_e32 v3, s46, v7
	s_nop 0
	v_cndmask_b32_e32 v251, v245, v1, vcc
	v_mul_f32_e32 v1, 0x3e38aa3b, v5
	v_cmp_le_u32_e32 vcc, v227, v131
	s_nop 1
	v_cndmask_b32_e32 v252, v245, v1, vcc
	v_cmp_le_u32_e32 vcc, v72, v131
	v_mul_f32_e32 v1, 0x3e38aa3b, v8
	s_nop 0
	v_cndmask_b32_e32 v215, v245, v2, vcc
	v_cmp_le_u32_e32 vcc, v69, v131
	s_nop 1
	v_cndmask_b32_e32 v34, v245, v3, vcc
	v_cmp_le_u32_e32 vcc, v228, v131
	v_mul_f32_e32 v2, s46, v10
	v_mul_f32_e32 v3, s46, v11
	s_nop 0
	v_cndmask_b32_e32 v137, v245, v1, vcc
	v_mul_f32_e32 v1, 0x3e38aa3b, v9
	v_cmp_le_u32_e32 vcc, v229, v131
	s_nop 1
	v_cndmask_b32_e32 v1, v245, v1, vcc
	v_cmp_le_u32_e32 vcc, v74, v131
	s_nop 1
	v_cndmask_b32_e32 v234, v245, v2, vcc
	v_cmp_le_u32_e32 vcc, v71, v131
	v_mul_f32_e32 v2, 0x3e38aa3b, v12
	s_nop 0
	v_cndmask_b32_e32 v75, v245, v3, vcc
	v_cmp_le_u32_e32 vcc, v230, v131
	s_nop 1
	v_cndmask_b32_e32 v82, v245, v2, vcc
	v_mul_f32_e32 v2, 0x3e38aa3b, v13
	v_cmp_le_u32_e32 vcc, v231, v131
	s_nop 1
	v_cndmask_b32_e32 v77, v245, v2, vcc
	v_mul_f32_e32 v2, s46, v14
	v_mul_f32_e32 v3, s46, v15
	v_cmp_le_u32_e32 vcc, v76, v131
	s_nop 1
	v_cndmask_b32_e32 v14, v245, v2, vcc
	v_cmp_le_u32_e32 vcc, v73, v131
	v_mul_f32_e32 v2, 0x3e38aa3b, v16
	s_nop 0
	v_cndmask_b32_e32 v15, v245, v3, vcc
	v_cmp_le_u32_e32 vcc, v232, v131
	s_nop 1
	v_cndmask_b32_e32 v16, v245, v2, vcc
	v_mul_f32_e32 v2, 0x3e38aa3b, v17
	v_cmp_le_u32_e32 vcc, v233, v131
	s_nop 1
	v_cndmask_b32_e32 v17, v245, v2, vcc
.LBB0_489:
	v_max3_f32 v2, v128, s61, v129
	v_max3_f32 v2, v2, v130, v134
	v_max3_f32 v2, v2, v135, v139
	v_max3_f32 v2, v2, v140, v141
	v_max3_f32 v2, v2, v142, v143
	v_max3_f32 v2, v2, v144, v145
	v_max3_f32 v2, v2, v146, v147
	v_max3_f32 v2, v2, v148, v149
	v_max3_f32 v2, v2, v121, v150
	v_max3_f32 v2, v2, v151, v152
	v_max3_f32 v2, v2, v153, v154
	v_max3_f32 v2, v2, v155, v156
	v_max3_f32 v2, v2, v157, v158
	v_max3_f32 v2, v2, v159, v160
	v_max3_f32 v2, v2, v161, v162
	v_max3_f32 v2, v2, v163, v164
	v_max3_f32 v2, v2, v166, v167
	v_max3_f32 v2, v2, v174, v175
	v_max3_f32 v2, v2, v190, v191
	v_max3_f32 v2, v2, v192, v193
	v_max3_f32 v2, v2, v194, v195
	v_max3_f32 v2, v2, v196, v197
	v_max3_f32 v2, v2, v247, v248
	v_max3_f32 v2, v2, v249, v250
	v_max3_f32 v2, v2, v165, v127
	v_max3_f32 v2, v2, v251, v252
	v_max3_f32 v2, v2, v215, v34
	v_max3_f32 v2, v2, v137, v1
	v_and_b32_e32 v4, 64, v246
	v_max3_f32 v2, v2, v234, v75
	v_xor_b32_e32 v3, 32, v246
	v_add_u32_e32 v4, 64, v4
	v_max3_f32 v2, v2, v82, v77
	v_cmp_lt_i32_e32 vcc, v3, v4
	v_max3_f32 v2, v2, v14, v15
	v_max3_f32 v2, v2, v16, v17
	v_cndmask_b32_e32 v3, v246, v3, vcc
	v_lshlrev_b32_e32 v41, 2, v3
	ds_bpermute_b32 v3, v41, v2
	s_waitcnt lgkmcnt(0)
	v_max_f32_e32 v3, v3, v3
	v_max_f32_e32 v2, v2, v3
	v_cmp_neq_f32_e32 vcc, s61, v2
	s_waitcnt vmcnt(3)
	s_nop 0
	v_cndmask_b32_e32 v30, 0, v2, vcc
	v_sub_f32_e32 v2, v128, v30
	v_exp_f32_e32 v12, v2
	v_sub_f32_e32 v2, v129, v30
	v_exp_f32_e32 v10, v2
	v_sub_f32_e32 v2, v130, v30
	v_exp_f32_e32 v13, v2
	v_sub_f32_e32 v2, v134, v30
	v_exp_f32_e32 v11, v2
	v_add_f32_e32 v2, 0, v12
	v_add_f32_e32 v2, v10, v2
	v_add_f32_e32 v2, v13, v2
	v_add_f32_e32 v3, v11, v2
	v_sub_f32_e32 v2, v135, v30
	v_exp_f32_e32 v8, v2
	v_sub_f32_e32 v2, v139, v30
	v_exp_f32_e32 v6, v2
	v_sub_f32_e32 v2, v140, v30
	v_exp_f32_e32 v4, v2
	v_sub_f32_e32 v2, v141, v30
	v_exp_f32_e32 v2, v2
	v_sub_f32_e32 v5, v142, v30
	v_add_f32_e32 v3, v8, v3
	s_waitcnt vmcnt(0)
; DI float fexp2(float x) { return __builtin_amdgcn_exp2f(x); }
; DI void cmp_task(const bf16_t* Z, const bf16_t* KCC, const bf16_t* VCT, bf16_t* OCMP, unsigned* selm, int b, int hk, int tg, int lane) {
;     ...
;     const float mu = (mx == NINF) ? 0.f : mx;
;     float sum = 0.f;
; #pragma unroll
;     for (int sub = 0; sub < 4; ++sub)
; #pragma unroll
;         for (int r = 0; r < 16; ++r) { p[sub][r] = fexp2(p[sub][r] - mu); sum += p[sub][r]; }
;     const float lt = sum + __shfl_xor(sum, 32); const float inv = lt > 0.f ? 1.0f / lt : 0.f;
; #pragma unroll
;     for (int sub = 0; sub < 4; ++sub)
; #pragma unroll
;         for (int r = 0; r < 16; ++r) p[sub][r] *= inv;
	v_exp_f32_e32 v18, v5
	v_sub_f32_e32 v5, v143, v30
	v_add_f32_e32 v3, v6, v3
	v_exp_f32_e32 v19, v5
	v_sub_f32_e32 v5, v144, v30
	v_add_f32_e32 v3, v4, v3
	v_exp_f32_e32 v20, v5
	v_sub_f32_e32 v5, v145, v30
	v_add_f32_e32 v3, v2, v3
	v_exp_f32_e32 v21, v5
	v_add_f32_e32 v3, v18, v3
	v_add_f32_e32 v3, v19, v3
	v_add_f32_e32 v3, v20, v3
	v_add_f32_e32 v22, v21, v3
	v_sub_f32_e32 v3, v146, v30
	v_exp_f32_e32 v9, v3
	v_sub_f32_e32 v3, v147, v30
	v_exp_f32_e32 v7, v3
	v_sub_f32_e32 v3, v148, v30
	v_exp_f32_e32 v5, v3
	v_sub_f32_e32 v3, v149, v30
	v_exp_f32_e32 v3, v3
	v_sub_f32_e32 v23, v121, v30
	v_add_f32_e32 v22, v9, v22
	v_exp_f32_e32 v168, v23
	v_sub_f32_e32 v23, v150, v30
	v_add_f32_e32 v22, v7, v22
	v_exp_f32_e32 v169, v23
	v_sub_f32_e32 v23, v151, v30
	v_add_f32_e32 v22, v5, v22
	v_exp_f32_e32 v170, v23
	v_sub_f32_e32 v23, v152, v30
	v_add_f32_e32 v22, v3, v22
	v_exp_f32_e32 v171, v23
	v_sub_f32_e32 v23, v153, v30
	v_add_f32_e32 v22, v168, v22
	v_exp_f32_e32 v172, v23
	v_sub_f32_e32 v23, v154, v30
	v_add_f32_e32 v22, v169, v22
	v_exp_f32_e32 v176, v23
	v_sub_f32_e32 v23, v155, v30
	v_add_f32_e32 v22, v170, v22
	v_exp_f32_e32 v180, v23
	v_sub_f32_e32 v23, v156, v30
	v_add_f32_e32 v22, v171, v22
	v_exp_f32_e32 v178, v23
	v_sub_f32_e32 v23, v157, v30
	v_add_f32_e32 v22, v172, v22
	v_exp_f32_e32 v182, v23
	v_sub_f32_e32 v23, v158, v30
	v_add_f32_e32 v22, v176, v22
	v_exp_f32_e32 v184, v23
	v_sub_f32_e32 v23, v159, v30
	v_add_f32_e32 v22, v180, v22
	v_exp_f32_e32 v186, v23
	v_sub_f32_e32 v23, v160, v30
	v_add_f32_e32 v22, v178, v22
	v_exp_f32_e32 v188, v23
	v_sub_f32_e32 v23, v161, v30
	v_add_f32_e32 v22, v182, v22
	v_exp_f32_e32 v173, v23
	v_sub_f32_e32 v23, v162, v30
	v_add_f32_e32 v22, v184, v22
	v_exp_f32_e32 v177, v23
	v_sub_f32_e32 v23, v163, v30
	v_add_f32_e32 v22, v186, v22
	v_exp_f32_e32 v181, v23
	v_sub_f32_e32 v23, v164, v30
	v_add_f32_e32 v22, v188, v22
	v_exp_f32_e32 v179, v23
	v_sub_f32_e32 v23, v166, v30
	v_add_f32_e32 v22, v173, v22
	v_exp_f32_e32 v183, v23
	v_sub_f32_e32 v23, v167, v30
	v_add_f32_e32 v22, v177, v22
	v_exp_f32_e32 v185, v23
	v_sub_f32_e32 v23, v174, v30
	v_add_f32_e32 v22, v181, v22
	v_exp_f32_e32 v187, v23
	v_sub_f32_e32 v23, v175, v30
	v_add_f32_e32 v22, v179, v22
	v_exp_f32_e32 v189, v23
	v_add_f32_e32 v22, v183, v22
	v_add_f32_e32 v22, v185, v22
	v_add_f32_e32 v22, v187, v22
	v_add_f32_e32 v23, v189, v22
	v_sub_f32_e32 v22, v190, v30
	v_exp_f32_e32 v22, v22
	v_sub_f32_e32 v24, v191, v30
	v_exp_f32_e32 v24, v24
	v_sub_f32_e32 v25, v192, v30
	v_exp_f32_e32 v26, v25
	v_sub_f32_e32 v25, v193, v30
	v_exp_f32_e32 v28, v25
	v_sub_f32_e32 v25, v194, v30
	v_add_f32_e32 v23, v22, v23
	v_exp_f32_e32 v200, v25
	v_sub_f32_e32 v25, v195, v30
	v_add_f32_e32 v23, v24, v23
	v_exp_f32_e32 v201, v25
	v_sub_f32_e32 v25, v196, v30
	v_add_f32_e32 v23, v26, v23
	v_exp_f32_e32 v198, v25
	v_sub_f32_e32 v25, v197, v30
	v_add_f32_e32 v23, v28, v23
	v_exp_f32_e32 v199, v25
	v_add_f32_e32 v23, v200, v23
	v_add_f32_e32 v23, v201, v23
	v_add_f32_e32 v23, v198, v23
	v_add_f32_e32 v31, v199, v23
	v_sub_f32_e32 v23, v247, v30
	v_exp_f32_e32 v23, v23
	v_sub_f32_e32 v25, v248, v30
	v_exp_f32_e32 v25, v25
	v_sub_f32_e32 v27, v249, v30
	v_exp_f32_e32 v27, v27
	v_sub_f32_e32 v29, v250, v30
	v_exp_f32_e32 v29, v29
	v_sub_f32_e32 v32, v165, v30
	v_add_f32_e32 v31, v23, v31
	v_exp_f32_e32 v154, v32
	v_sub_f32_e32 v32, v127, v30
	v_add_f32_e32 v31, v25, v31
	v_exp_f32_e32 v155, v32
	v_sub_f32_e32 v32, v251, v30
	v_add_f32_e32 v31, v27, v31
	v_exp_f32_e32 v156, v32
	v_sub_f32_e32 v32, v252, v30
	v_add_f32_e32 v31, v29, v31
	v_exp_f32_e32 v157, v32
	v_sub_f32_e32 v32, v215, v30
	v_add_f32_e32 v31, v154, v31
	v_exp_f32_e32 v164, v32
	v_add_f32_e32 v31, v155, v31
	v_sub_f32_e32 v32, v34, v30
	v_add_f32_e32 v31, v156, v31
	v_exp_f32_e32 v162, v32
	v_sub_f32_e32 v32, v137, v30
	v_add_f32_e32 v31, v157, v31
	v_exp_f32_e32 v160, v32
	v_sub_f32_e32 v1, v1, v30
	v_exp_f32_e32 v158, v1
	v_add_f32_e32 v1, v164, v31
	v_sub_f32_e32 v31, v234, v30
	v_exp_f32_e32 v165, v31
	v_sub_f32_e32 v31, v75, v30
	v_add_f32_e32 v1, v162, v1
	v_exp_f32_e32 v163, v31
	v_sub_f32_e32 v31, v82, v30
	v_add_f32_e32 v1, v160, v1
	v_exp_f32_e32 v161, v31
	v_sub_f32_e32 v31, v77, v30
	v_add_f32_e32 v1, v158, v1
	v_exp_f32_e32 v159, v31
	v_sub_f32_e32 v14, v14, v30
	v_add_f32_e32 v1, v165, v1
	v_exp_f32_e32 v166, v14
	v_sub_f32_e32 v14, v15, v30
	v_add_f32_e32 v1, v163, v1
	v_exp_f32_e32 v167, v14
	v_sub_f32_e32 v14, v16, v30
	v_add_f32_e32 v1, v161, v1
	v_exp_f32_e32 v174, v14
	v_sub_f32_e32 v14, v17, v30
	v_add_f32_e32 v1, v159, v1
	v_exp_f32_e32 v175, v14
	v_add_f32_e32 v1, v166, v1
	v_add_f32_e32 v1, v167, v1
	v_add_f32_e32 v1, v174, v1
	v_add_f32_e32 v1, v175, v1
	ds_bpermute_b32 v14, v41, v1
	v_lshl_add_u64 v[190:191], v[78:79], 0, s[8:9]
	v_lshlrev_b32_e32 v196, 1, v136
	v_lshlrev_b32_e32 v192, 1, v80
	s_waitcnt lgkmcnt(0)
	v_add_f32_e32 v1, v1, v14
	v_div_scale_f32 v14, s[78:79], v1, v1, 1.0
	v_rcp_f32_e32 v15, v14
	s_nop 0
	v_fma_f32 v16, -v14, v15, 1.0
	v_fmac_f32_e32 v15, v16, v15
	v_div_scale_f32 v16, vcc, 1.0, v1, 1.0
	v_mul_f32_e32 v17, v16, v15
	v_fma_f32 v30, -v14, v17, v16
	v_fmac_f32_e32 v17, v30, v15
	v_fma_f32 v14, -v14, v17, v16
	v_div_fmas_f32 v14, v14, v15, v17
	v_div_fixup_f32 v14, v14, v1, 1.0
	v_cmp_lt_f32_e32 vcc, 0, v1
	s_nop 1
	v_cndmask_b32_e32 v194, 0, v14, vcc
	v_mul_f32_e32 v130, v12, v194
	v_mul_f32_e32 v131, v13, v194
	v_mul_f32_e32 v134, v10, v194
	v_mul_f32_e32 v135, v11, v194
	v_mul_f32_e32 v124, v18, v194
	v_mul_f32_e32 v125, v19, v194
	v_mul_f32_e32 v126, v20, v194
	v_mul_f32_e32 v127, v21, v194
	v_mul_f32_e32 v140, v22, v194
	v_mul_f32_e32 v141, v23, v194
	v_mul_f32_e32 v142, v8, v194
	v_mul_f32_e32 v143, v9, v194
	v_mul_f32_e32 v144, v24, v194
	v_mul_f32_e32 v145, v25, v194
	v_mul_f32_e32 v148, v6, v194
	v_mul_f32_e32 v149, v7, v194
	v_mul_f32_e32 v146, v26, v194
	v_mul_f32_e32 v147, v27, v194
	v_mul_f32_e32 v150, v4, v194
	v_mul_f32_e32 v151, v5, v194
	v_mul_f32_e32 v128, v28, v194
	v_mul_f32_e32 v129, v29, v194
	v_mul_f32_e32 v152, v2, v194
	v_mul_f32_e32 v153, v3, v194
	v_mbcnt_lo_u32_b32 v215, -1, 0
	v_mbcnt_hi_u32_b32 v215, -1, v215
	v_lshrrev_b32_e32 v77, 5, v215
	v_and_b32_e32 v215, 31, v215
	v_lshlrev_b32_e32 v215, 4, v215
	v_lshl_or_b32 v215, v77, 3, v215
	v_add_u32_e32 v215, s99, v215
	s_waitcnt vmcnt(0)
	s_andn2_b64 vcc, exec, s[10:11]
	s_cbranch_vccnz .LBB0_491
; #define MFMA32(a, b, c) __builtin_amdgcn_mfma_f32_32x32x16_bf16((a), (b), (c), 0, 0, 0)
; DI void cmp_task(const bf16_t* Z, const bf16_t* KCC, const bf16_t* VCT, bf16_t* OCMP, unsigned* selm, int b, int hk, int tg, int lane) {
;     ...
;     f32x16 o0 = f16zero(), o1 = f16zero();
; #pragma unroll
;     for (int sub = 0; sub < 4; ++sub) if (sub < nsub) {
; #pragma unroll
;         for (int s2 = 0; s2 < 2; ++s2) {
;             const bf16x8 pf = pack8(p[sub], s2);
; #pragma unroll
;             for (int dt = 0; dt < 2; ++dt) {
;                 const bf16_t* wp = vt + (size_t)(32 * dt + r32) * 128 + 32 * sub + 16 * s2 + 4 * h;
;                 const u32x2 lo = *(const u32x2*)wp, hi = *(const u32x2*)(wp + 8);
;                 const u32x4 w4 = {lo.x, lo.y, hi.x, hi.y}; const bf16x8 vf = __builtin_bit_cast(bf16x8, w4);
;                 if (dt == 0) o0 = MFMA32(vf, pf, o0); else o1 = MFMA32(vf, pf, o1);
;             }
	v_mov_b32_e32 v197, v43
	v_lshl_add_u64 v[96:97], v[190:191], 0, v[196:197]
	ds_read_b64 v[2:3], v215 offset:0
	ds_read_b64 v[4:5], v215 offset:512
	v_mov_b32_e32 v193, v43
	v_lshl_add_u64 v[234:235], v[190:191], 0, v[192:193]
	ds_read_b64 v[22:23], v215 offset:8192
	ds_read_b64 v[24:25], v215 offset:8704
	ds_read_b64 v[94:95], v215 offset:1024
	s_nop 0
	ds_read_b64 v[96:97], v215 offset:1536
	v_cvt_pk_bf16_f32 v18, v130, v134
	v_cvt_pk_bf16_f32 v19, v131, v135
	v_cvt_pk_bf16_f32 v20, v142, v148
	v_cvt_pk_bf16_f32 v21, v150, v152
	v_cvt_pk_bf16_f32 v248, v124, v125
	v_cvt_pk_bf16_f32 v249, v126, v127
	v_cvt_pk_bf16_f32 v250, v143, v149
	v_cvt_pk_bf16_f32 v251, v151, v153
	s_waitcnt lgkmcnt(4)
	v_mfma_f32_32x32x16_bf16 v[2:17], v[2:5], v[18:21], 0
	s_waitcnt lgkmcnt(0)
	v_mfma_f32_32x32x16_bf16 v[2:17], v[94:97], v[248:251], v[2:17]
	ds_read_b64 v[94:95], v215 offset:9216
	ds_read_b64 v[96:97], v215 offset:9728
	v_mfma_f32_32x32x16_bf16 v[18:33], v[22:25], v[18:21], 0
	s_waitcnt lgkmcnt(0)
	v_mfma_f32_32x32x16_bf16 v[18:33], v[94:97], v[248:251], v[18:33]
	s_branch .LBB0_492

; #define MFMA32(a, b, c) __builtin_amdgcn_mfma_f32_32x32x16_bf16((a), (b), (c), 0, 0, 0)
; DI void cmp_task(const bf16_t* Z, const bf16_t* KCC, const bf16_t* VCT, bf16_t* OCMP, unsigned* selm, int b, int hk, int tg, int lane) {
;     ...
; #pragma unroll
;     for (int sub = 0; sub < 4; ++sub)
; #pragma unroll
;         for (int r = 0; r < 16; ++r) p[sub][r] *= inv;
;     f32x16 o0 = f16zero(), o1 = f16zero();
; #pragma unroll
;     for (int sub = 0; sub < 4; ++sub) if (sub < nsub) {
; #pragma unroll
;         for (int s2 = 0; s2 < 2; ++s2) {
;             const bf16x8 pf = pack8(p[sub], s2);
; #pragma unroll
;             for (int dt = 0; dt < 2; ++dt) {
;                 const bf16_t* wp = vt + (size_t)(32 * dt + r32) * 128 + 32 * sub + 16 * s2 + 4 * h;
;                 const u32x2 lo = *(const u32x2*)wp, hi = *(const u32x2*)(wp + 8);
;                 const u32x4 w4 = {lo.x, lo.y, hi.x, hi.y}; const bf16x8 vf = __builtin_bit_cast(bf16x8, w4);
;                 if (dt == 0) o0 = MFMA32(vf, pf, o0); else o1 = MFMA32(vf, pf, o1);
;             }
;         }
;     }
.LBB0_492:
	v_mov_b32_e32 v195, v194
	v_mul_f32_e32 v168, v168, v194
	v_mul_f32_e32 v169, v169, v195
	v_mul_f32_e32 v170, v170, v194
	v_mul_f32_e32 v171, v171, v195
	v_mul_f32_e32 v172, v172, v194
	v_mul_f32_e32 v173, v173, v195
	v_mul_f32_e32 v176, v176, v194
	v_mul_f32_e32 v177, v177, v195
	v_mul_f32_e32 v180, v180, v194
	v_mul_f32_e32 v181, v181, v195
	v_mul_f32_e32 v178, v178, v194
	v_mul_f32_e32 v179, v179, v195
	v_mul_f32_e32 v182, v182, v194
	v_mul_f32_e32 v183, v183, v195
	v_mul_f32_e32 v184, v184, v194
	v_mul_f32_e32 v185, v185, v195
	v_mul_f32_e32 v186, v186, v194
	v_mul_f32_e32 v187, v187, v195
	s_andn2_b64 vcc, exec, s[48:49]
	v_mul_f32_e32 v188, v188, v194
	v_mul_f32_e32 v189, v189, v195
	s_cbranch_vccnz .LBB0_494
	v_mov_b32_e32 v197, v43
	v_lshl_add_u64 v[234:235], v[190:191], 0, v[196:197]
	ds_read_b64 v[248:249], v215 offset:2048
	ds_read_b64 v[250:251], v215 offset:2560
	v_mov_b32_e32 v193, v43
	v_cvt_pk_bf16_f32 v94, v168, v169
	v_cvt_pk_bf16_f32 v95, v170, v171
	v_cvt_pk_bf16_f32 v96, v172, v176
	v_cvt_pk_bf16_f32 v97, v180, v178
	v_lshl_add_u64 v[34:35], v[190:191], 0, v[192:193]
	s_waitcnt lgkmcnt(0)
	v_mfma_f32_32x32x16_bf16 v[2:17], v[248:251], v[94:97], v[2:17]
	ds_read_b64 v[248:249], v215 offset:10240
	ds_read_b64 v[250:251], v215 offset:10752
	s_waitcnt lgkmcnt(0)
	v_mfma_f32_32x32x16_bf16 v[18:33], v[248:251], v[94:97], v[18:33]
	ds_read_b64 v[248:249], v215 offset:3072
	ds_read_b64 v[250:251], v215 offset:3584
	v_cvt_pk_bf16_f32 v94, v182, v184
	v_cvt_pk_bf16_f32 v95, v186, v188
	v_cvt_pk_bf16_f32 v96, v173, v177
	v_cvt_pk_bf16_f32 v97, v181, v179
	s_waitcnt lgkmcnt(0)
	s_nop 0
	v_mfma_f32_32x32x16_bf16 v[2:17], v[248:251], v[94:97], v[2:17]
	ds_read_b64 v[248:249], v215 offset:11264
	ds_read_b64 v[250:251], v215 offset:11776
	s_waitcnt lgkmcnt(0)
	v_mfma_f32_32x32x16_bf16 v[18:33], v[248:251], v[94:97], v[18:33]
.LBB0_494:
	v_mul_f32_e32 v200, v200, v194
	v_mul_f32_e32 v201, v201, v195
	s_andn2_b64 vcc, exec, s[50:51]
	v_mul_f32_e32 v198, v198, v194
	v_mul_f32_e32 v199, v199, v195
	s_cbranch_vccnz .LBB0_496
	v_mov_b32_e32 v197, v43
	v_lshl_add_u64 v[34:35], v[190:191], 0, v[196:197]
	ds_read_b64 v[248:249], v215 offset:4096
	ds_read_b64 v[250:251], v215 offset:4608
	v_mov_b32_e32 v193, v43
	v_cvt_pk_bf16_f32 v94, v183, v185
	v_cvt_pk_bf16_f32 v95, v187, v189
	v_cvt_pk_bf16_f32 v96, v140, v144
	v_cvt_pk_bf16_f32 v97, v146, v128
	v_lshl_add_u64 v[234:235], v[190:191], 0, v[192:193]
	s_waitcnt lgkmcnt(0)
	v_mfma_f32_32x32x16_bf16 v[2:17], v[248:251], v[94:97], v[2:17]
	ds_read_b64 v[248:249], v215 offset:12288
	ds_read_b64 v[250:251], v215 offset:12800
	s_waitcnt lgkmcnt(0)
	v_mfma_f32_32x32x16_bf16 v[18:33], v[248:251], v[94:97], v[18:33]
	ds_read_b64 v[248:249], v215 offset:5120
	ds_read_b64 v[250:251], v215 offset:5632
	v_cvt_pk_bf16_f32 v94, v200, v201
	v_cvt_pk_bf16_f32 v95, v198, v199
	v_cvt_pk_bf16_f32 v96, v141, v145
	v_cvt_pk_bf16_f32 v97, v147, v129
	s_waitcnt lgkmcnt(0)
	s_nop 0
	v_mfma_f32_32x32x16_bf16 v[2:17], v[248:251], v[94:97], v[2:17]
	ds_read_b64 v[248:249], v215 offset:13312
	ds_read_b64 v[250:251], v215 offset:13824
	s_waitcnt lgkmcnt(0)
	v_mfma_f32_32x32x16_bf16 v[18:33], v[248:251], v[94:97], v[18:33]
.LBB0_496:
	v_mul_f32_e32 v154, v154, v194
	v_mul_f32_e32 v155, v155, v195
	v_mul_f32_e32 v156, v156, v194
	v_mul_f32_e32 v157, v157, v195
	v_mul_f32_e32 v164, v164, v194
	v_mul_f32_e32 v165, v165, v195
	v_mul_f32_e32 v162, v162, v194
	v_mul_f32_e32 v163, v163, v195
	v_mul_f32_e32 v160, v160, v194
	v_mul_f32_e32 v161, v161, v195
	s_andn2_b64 vcc, exec, s[52:53]
	v_mul_f32_e32 v158, v158, v194
	v_mul_f32_e32 v159, v159, v195
	s_cbranch_vccnz .LBB0_498
	v_mov_b32_e32 v197, v43
	v_mul_f32_e32 v34, v166, v194
	v_mul_f32_e32 v35, v167, v195
	v_mul_f32_e32 v166, v174, v194
	v_mul_f32_e32 v167, v175, v195
	v_lshl_add_u64 v[174:175], v[190:191], 0, v[196:197]
	ds_read_b64 v[194:195], v215 offset:6144
	ds_read_b64 v[196:197], v215 offset:6656
	v_cvt_pk_bf16_f32 v94, v154, v155
	v_cvt_pk_bf16_f32 v95, v156, v157
	v_cvt_pk_bf16_f32 v96, v164, v162
	v_cvt_pk_bf16_f32 v97, v160, v158
	v_mov_b32_e32 v193, v43
	s_waitcnt lgkmcnt(0)
	v_mfma_f32_32x32x16_bf16 v[2:17], v[194:197], v[94:97], v[2:17]
	v_lshl_add_u64 v[194:195], v[190:191], 0, v[192:193]
	ds_read_b64 v[190:191], v215 offset:14336
	ds_read_b64 v[192:193], v215 offset:14848
	s_waitcnt lgkmcnt(0)
	v_mfma_f32_32x32x16_bf16 v[18:33], v[190:193], v[94:97], v[18:33]
	ds_read_b64 v[190:191], v215 offset:7168
	ds_read_b64 v[192:193], v215 offset:7680
	v_cvt_pk_bf16_f32 v94, v165, v163
	v_cvt_pk_bf16_f32 v95, v161, v159
	v_cvt_pk_bf16_f32 v96, v34, v35
	v_cvt_pk_bf16_f32 v97, v166, v167
	s_waitcnt lgkmcnt(0)
	s_nop 0
	v_mfma_f32_32x32x16_bf16 v[2:17], v[190:193], v[94:97], v[2:17]
	ds_read_b64 v[190:191], v215 offset:15360
	ds_read_b64 v[192:193], v215 offset:15872
	s_waitcnt lgkmcnt(0)
	v_mfma_f32_32x32x16_bf16 v[18:33], v[190:193], v[94:97], v[18:33]
; DI unsigned pk2(float lo, float hi) { const f32x2 v = {lo, hi}; const bf16x2_t b = __builtin_convertvector(v, bf16x2_t); return __builtin_bit_cast(unsigned, b); }
; DI float dpp_x1(float v) { return __builtin_bit_cast(float, __builtin_amdgcn_update_dpp(0, __builtin_bit_cast(int, v), 0xB1, 0xf, 0xf, true)); }
; DI float dpp_x2(float v) { return __builtin_bit_cast(float, __builtin_amdgcn_update_dpp(0, __builtin_bit_cast(int, v), 0x4E, 0xf, 0xf, true)); }
; DI void store_y(bf16_t* dst, const f32x16& y0, const f32x16& y1, int h) {
; #pragma unroll
;     for (int mm = 0; mm < 4; ++mm) {
;         u32x2 w0; w0.x = pk2(y0[4 * mm], y0[4 * mm + 1]); w0.y = pk2(y0[4 * mm + 2], y0[4 * mm + 3]);
;         u32x2 w1; w1.x = pk2(y1[4 * mm], y1[4 * mm + 1]); w1.y = pk2(y1[4 * mm + 2], y1[4 * mm + 3]);
;         *(u32x2*)(dst + 8 * mm + 4 * h) = w0; *(u32x2*)(dst + 32 + 8 * mm + 4 * h) = w1;
;     }
; }
; DI void cmp_task(const bf16_t* Z, const bf16_t* KCC, const bf16_t* VCT, bf16_t* OCMP, unsigned* selm, int b, int hk, int tg, int lane) {
;     ...
;     store_y(OCMP + grow * 512 + head * 64, o0, o1, h);
;     const int cur = tg >> 3; unsigned mask;
;     if (cur <= 7) mask = (2u << cur) - 1u;
;     else {
;         float a[4][4], PL[4][4];
; #pragma unroll
;         for (int T = 0; T < 4; ++T)
; #pragma unroll
;             for (int mm = 0; mm < 4; ++mm) { a[T][mm] = (p[T][4 * mm] + p[T][4 * mm + 1]) + (p[T][4 * mm + 2] + p[T][4 * mm + 3]); PL[T][mm] = __shfl_xor(p[T][4 * mm + 3], 32); }
; #pragma unroll
;         for (int T = 0; T < 4; ++T)
; #pragma unroll
;             for (int mm = 0; mm < 4; ++mm) { const float prev = mm > 0 ? PL[T][mm - 1] : (T > 0 ? PL[T - 1][3] : 0.f); a[T][mm] += h ? PL[T][mm] : prev; }
;         float ev[4][4], od[4][4], mine[4];
; #pragma unroll
;         for (int T = 0; T < 4; ++T)
; #pragma unroll
;             for (int mm = 0; mm < 4; ++mm) {
;                 float v = a[T][mm]; v += dpp_x1(v); v += dpp_x2(v);
;                 const int j = 8 * T + 2 * mm + h; v = (j >= 1 && j <= cur - 2) ? v : -1.0f;
;                 const float vx = __shfl_xor(v, 32);
;                 ev[T][mm] = h ? vx : v; od[T][mm] = h ? v : vx; a[T][mm] = v;
.LBB0_498:
	v_lshlrev_b64 v[34:35], 10, v[122:123]
	v_lshl_add_u64 v[34:35], s[18:19], 0, v[34:35]
	v_lshl_add_u64 v[34:35], v[34:35], 0, v[42:43]
	v_mov_b32_e32 v139, v43
	v_lshl_add_u64 v[34:35], v[34:35], 0, v[138:139]
	s_nop 2
	v_cvt_pk_bf16_f32 v2, v2, v3
	v_cvt_pk_bf16_f32 v3, v4, v5
	s_nop 1
	v_cvt_pk_bf16_f32 v4, v18, v19
	v_cvt_pk_bf16_f32 v5, v20, v21
	global_store_dwordx2 v[34:35], v[2:3], off
	global_store_dwordx2 v[34:35], v[4:5], off offset:64
	v_cvt_pk_bf16_f32 v2, v6, v7
	v_cvt_pk_bf16_f32 v3, v8, v9
	v_cvt_pk_bf16_f32 v4, v22, v23
	v_cvt_pk_bf16_f32 v5, v24, v25
	global_store_dwordx2 v[34:35], v[2:3], off offset:16
	global_store_dwordx2 v[34:35], v[4:5], off offset:80
	v_cvt_pk_bf16_f32 v2, v10, v11
	v_cvt_pk_bf16_f32 v3, v12, v13
	s_lshr_b32 s48, s54, 3
	v_cvt_pk_bf16_f32 v4, v26, v27
	v_cvt_pk_bf16_f32 v5, v28, v29
	global_store_dwordx2 v[34:35], v[2:3], off offset:32
	global_store_dwordx2 v[34:35], v[4:5], off offset:96
	v_cvt_pk_bf16_f32 v2, v14, v15
	v_cvt_pk_bf16_f32 v3, v16, v17
	s_cmp_gt_u32 s54, 63
	s_mov_b64 s[8:9], -1
	v_cvt_pk_bf16_f32 v4, v30, v31
	v_cvt_pk_bf16_f32 v5, v32, v33
	global_store_dwordx2 v[34:35], v[2:3], off offset:48
	global_store_dwordx2 v[34:35], v[4:5], off offset:112
	s_cbranch_scc0 .LBB0_564
	ds_bpermute_b32 v14, v41, v135
	ds_bpermute_b32 v15, v41, v152
	ds_bpermute_b32 v17, v41, v127
	v_add_f32_e32 v19, v198, v199
	v_add_f32_e32 v20, v200, v201
	ds_bpermute_b32 v18, v41, v128
	v_add_f32_e32 v19, v20, v19
	ds_bpermute_b32 v20, v41, v199
	v_add_f32_e32 v2, v130, v134
	v_add_f32_e32 v3, v131, v135
	ds_bpermute_b32 v27, v41, v153
	v_add_f32_e32 v1, v2, v3
	v_add_f32_e32 v2, v140, v144
	v_add_f32_e32 v3, v141, v145
	v_add_f32_e32 v6, v146, v128
	v_add_f32_e32 v7, v147, v129
	ds_bpermute_b32 v75, v41, v189
	ds_bpermute_b32 v77, v41, v129
	v_add_f32_e32 v10, v126, v127
	v_add_f32_e32 v11, v124, v125
	v_add_f32_e32 v2, v2, v6
	v_add_f32_e32 v3, v3, v7
	s_waitcnt lgkmcnt(7)
	v_cndmask_b32_e64 v6, v14, 0, s[4:5]
	v_add_f32_e32 v16, v11, v10
	v_add_f32_e32 v1, v1, v6
	s_waitcnt lgkmcnt(5)
	v_cndmask_b32_e64 v6, v17, v15, s[4:5]
	v_add_f32_e32 v4, v142, v148
	v_add_f32_e32 v5, v143, v149
	v_add_f32_e32 v8, v150, v152
	v_add_f32_e32 v9, v151, v153
	v_add_f32_e32 v30, v16, v6
	s_waitcnt lgkmcnt(3)
	v_cndmask_b32_e64 v6, v20, v18, s[4:5]
	v_add_f32_e32 v4, v4, v8
	v_add_f32_e32 v5, v5, v9
	v_add_f32_e32 v124, v19, v6
	s_waitcnt lgkmcnt(2)
	v_cndmask_b32_e64 v7, v27, v17, s[4:5]
	v_cndmask_b32_e64 v6, v15, v14, s[4:5]
	s_waitcnt lgkmcnt(1)
	v_cndmask_b32_e64 v8, v18, v75, s[4:5]
	s_waitcnt lgkmcnt(0)
	v_cndmask_b32_e64 v9, v77, v20, s[4:5]
	v_add_f32_e32 v4, v4, v6
	v_add_f32_e32 v5, v5, v7
	v_add_f32_e32 v2, v2, v8
	v_add_f32_e32 v3, v3, v9
	s_add_i32 s10, s48, -2
	v_mov_b32_dpp v6, v4 quad_perm:[1,0,3,2] row_mask:0xf bank_mask:0xf bound_ctrl:1
	v_mov_b32_dpp v7, v5 quad_perm:[1,0,3,2] row_mask:0xf bank_mask:0xf bound_ctrl:1
	v_mov_b32_dpp v8, v2 quad_perm:[1,0,3,2] row_mask:0xf bank_mask:0xf bound_ctrl:1
	v_mov_b32_dpp v9, v3 quad_perm:[1,0,3,2] row_mask:0xf bank_mask:0xf bound_ctrl:1
	v_add_f32_e32 v4, v4, v6
	v_add_f32_e32 v5, v5, v7
	v_add_f32_e32 v2, v2, v8
	v_add_f32_e32 v3, v3, v9
	ds_bpermute_b32 v32, v41, v171
	v_mov_b32_dpp v6, v4 quad_perm:[2,3,0,1] row_mask:0xf bank_mask:0xf bound_ctrl:1
	v_mov_b32_dpp v7, v5 quad_perm:[2,3,0,1] row_mask:0xf bank_mask:0xf bound_ctrl:1
	ds_bpermute_b32 v26, v41, v178
	ds_bpermute_b32 v31, v41, v188
	ds_bpermute_b32 v33, v41, v179
	v_cmp_lt_i32_e32 vcc, s10, v133
	v_add_f32_dpp v1, v1, v1 quad_perm:[1,0,3,2] row_mask:0xf bank_mask:0xf bound_ctrl:1
	v_mov_b32_dpp v8, v2 quad_perm:[2,3,0,1] row_mask:0xf bank_mask:0xf bound_ctrl:1
	v_mov_b32_dpp v9, v3 quad_perm:[2,3,0,1] row_mask:0xf bank_mask:0xf bound_ctrl:1
	v_add_f32_e32 v4, v4, v6
	v_add_f32_e32 v5, v5, v7
	v_or_b32_e32 v7, 22, v133
	v_add_f32_dpp v1, v1, v1 quad_perm:[2,3,0,1] row_mask:0xf bank_mask:0xf bound_ctrl:1
	s_or_b64 s[8:9], s[4:5], vcc
	v_add_f32_e32 v2, v2, v8
	v_add_f32_e32 v3, v3, v9
	v_cmp_ge_i32_e32 vcc, s10, v7
	v_cndmask_b32_e64 v15, v1, -1.0, s[8:9]
	v_or_b32_e32 v1, 6, v133
	v_cndmask_b32_e32 v3, -1.0, v3, vcc
	v_cmp_ge_i32_e32 vcc, s10, v36
	v_add_f32_e32 v10, v170, v171
	v_add_f32_e32 v11, v168, v169
	v_cndmask_b32_e32 v2, -1.0, v2, vcc
	v_cmp_ge_i32_e32 vcc, s10, v1
	v_or_b32_e32 v6, 2, v133
	v_add_f32_e32 v29, v11, v10
	v_add_f32_e32 v10, v172, v176
	v_add_f32_e32 v11, v173, v177
	v_add_f32_e32 v12, v180, v178
	v_add_f32_e32 v13, v181, v179
	v_cndmask_b32_e32 v5, -1.0, v5, vcc
	v_cmp_ge_i32_e32 vcc, s10, v6
	v_or_b32_e32 v6, 4, v133
	s_waitcnt lgkmcnt(0)
; DI float dpp_x1(float v) { return __builtin_bit_cast(float, __builtin_amdgcn_update_dpp(0, __builtin_bit_cast(int, v), 0xB1, 0xf, 0xf, true)); }
; DI float dpp_x2(float v) { return __builtin_bit_cast(float, __builtin_amdgcn_update_dpp(0, __builtin_bit_cast(int, v), 0x4E, 0xf, 0xf, true)); }
; DI void cmp_task(const bf16_t* Z, const bf16_t* KCC, const bf16_t* VCT, bf16_t* OCMP, unsigned* selm, int b, int hk, int tg, int lane) {
;     ...
; #pragma unroll
;         for (int T = 0; T < 4; ++T)
; #pragma unroll
;             for (int mm = 0; mm < 4; ++mm) { a[T][mm] = (p[T][4 * mm] + p[T][4 * mm + 1]) + (p[T][4 * mm + 2] + p[T][4 * mm + 3]); PL[T][mm] = __shfl_xor(p[T][4 * mm + 3], 32); }
; #pragma unroll
;         for (int T = 0; T < 4; ++T)
; #pragma unroll
;             for (int mm = 0; mm < 4; ++mm) { const float prev = mm > 0 ? PL[T][mm - 1] : (T > 0 ? PL[T - 1][3] : 0.f); a[T][mm] += h ? PL[T][mm] : prev; }
;         float ev[4][4], od[4][4], mine[4];
; #pragma unroll
;         for (int T = 0; T < 4; ++T)
; #pragma unroll
;             for (int mm = 0; mm < 4; ++mm) {
;                 float v = a[T][mm]; v += dpp_x1(v); v += dpp_x2(v);
;                 const int j = 8 * T + 2 * mm + h; v = (j >= 1 && j <= cur - 2) ? v : -1.0f;
;                 const float vx = __shfl_xor(v, 32);
;                 ev[T][mm] = h ? vx : v; od[T][mm] = h ? v : vx; a[T][mm] = v;
;             }
; #pragma unroll
;         for (int mm = 0; mm < 4; ++mm) mine[mm] = g == 0 ? a[0][mm] : g == 1 ? a[1][mm] : g == 2 ? a[2][mm] : a[3][mm];
	v_cndmask_b32_e64 v9, v33, v31, s[4:5]
	v_cndmask_b32_e32 v4, -1.0, v4, vcc
	v_cmp_ge_i32_e32 vcc, s10, v6
	v_add_f32_e32 v6, v10, v12
	v_add_f32_e32 v7, v11, v13
	v_cndmask_b32_e64 v8, v26, v32, s[4:5]
	v_add_f32_e32 v6, v6, v8
	v_add_f32_e32 v7, v7, v9
	v_add_f32_dpp v1, v30, v30 quad_perm:[1,0,3,2] row_mask:0xf bank_mask:0xf bound_ctrl:1
	v_add_f32_e32 v22, v182, v184
	v_add_f32_e32 v23, v183, v185
	v_mov_b32_dpp v8, v6 quad_perm:[1,0,3,2] row_mask:0xf bank_mask:0xf bound_ctrl:1
	v_mov_b32_dpp v9, v7 quad_perm:[1,0,3,2] row_mask:0xf bank_mask:0xf bound_ctrl:1
	v_add_f32_dpp v1, v1, v1 quad_perm:[2,3,0,1] row_mask:0xf bank_mask:0xf bound_ctrl:1
	v_add_f32_e32 v6, v6, v8
	v_add_f32_e32 v7, v7, v9
	v_cndmask_b32_e32 v19, -1.0, v1, vcc
	v_or_b32_e32 v1, 14, v133
	v_mov_b32_dpp v8, v6 quad_perm:[2,3,0,1] row_mask:0xf bank_mask:0xf bound_ctrl:1
	v_mov_b32_dpp v9, v7 quad_perm:[2,3,0,1] row_mask:0xf bank_mask:0xf bound_ctrl:1
	v_add_f32_e32 v6, v6, v8
	v_add_f32_e32 v7, v7, v9
	v_cmp_ge_i32_e32 vcc, s10, v1
	v_or_b32_e32 v8, 10, v133
	v_add_f32_e32 v24, v186, v188
	v_add_f32_e32 v25, v187, v189
	v_cndmask_b32_e32 v9, -1.0, v7, vcc
	v_cmp_ge_i32_e32 vcc, s10, v8
	v_add_f32_e32 v10, v22, v24
	v_add_f32_e32 v11, v23, v25
	v_cndmask_b32_e64 v7, v75, v33, s[4:5]
	v_cndmask_b32_e32 v8, -1.0, v6, vcc
	v_cndmask_b32_e64 v6, v31, v26, s[4:5]
	v_add_f32_e32 v6, v10, v6
	v_add_f32_e32 v7, v11, v7
	v_or_b32_e32 v1, 16, v133
	ds_bpermute_b32 v96, v41, v157
	v_mov_b32_dpp v10, v6 quad_perm:[1,0,3,2] row_mask:0xf bank_mask:0xf bound_ctrl:1
	v_mov_b32_dpp v11, v7 quad_perm:[1,0,3,2] row_mask:0xf bank_mask:0xf bound_ctrl:1
	v_add_f32_e32 v6, v6, v10
	v_add_f32_e32 v7, v7, v11
	ds_bpermute_b32 v97, v41, v158
	ds_bpermute_b32 v121, v41, v159
	v_mov_b32_dpp v10, v6 quad_perm:[2,3,0,1] row_mask:0xf bank_mask:0xf bound_ctrl:1
	v_mov_b32_dpp v11, v7 quad_perm:[2,3,0,1] row_mask:0xf bank_mask:0xf bound_ctrl:1
	v_add_f32_e32 v6, v6, v10
	v_add_f32_e32 v7, v7, v11
	v_cmp_ge_i32_e32 vcc, s10, v1
	v_or_b32_e32 v10, 12, v133
	v_cndmask_b32_e64 v1, v32, v27, s[4:5]
	v_cndmask_b32_e32 v11, -1.0, v7, vcc
	v_cmp_ge_i32_e32 vcc, s10, v10
	v_add_f32_e32 v1, v29, v1
	v_add_f32_e32 v34, v164, v162
	v_add_f32_e32 v35, v165, v163
	v_cndmask_b32_e32 v10, -1.0, v6, vcc
	v_add_f32_dpp v1, v1, v1 quad_perm:[1,0,3,2] row_mask:0xf bank_mask:0xf bound_ctrl:1
	v_or_b32_e32 v6, 8, v133
	v_cmp_ge_i32_e32 vcc, s10, v6
	v_add_f32_dpp v1, v1, v1 quad_perm:[2,3,0,1] row_mask:0xf bank_mask:0xf bound_ctrl:1
	v_add_f32_e32 v94, v160, v158
	v_add_f32_e32 v95, v161, v159
	v_cndmask_b32_e32 v24, -1.0, v1, vcc
	v_add_f32_dpp v1, v124, v124 quad_perm:[1,0,3,2] row_mask:0xf bank_mask:0xf bound_ctrl:1
	v_add_f32_e32 v21, v156, v157
	v_add_f32_e32 v28, v154, v155
	v_add_f32_dpp v1, v1, v1 quad_perm:[2,3,0,1] row_mask:0xf bank_mask:0xf bound_ctrl:1
	v_cmp_ge_i32_e32 vcc, s10, v84
	v_add_f32_e32 v6, v34, v94
	v_add_f32_e32 v7, v35, v95
	s_waitcnt lgkmcnt(0)
	v_cndmask_b32_e64 v13, v121, v97, s[4:5]
	v_cndmask_b32_e64 v12, v97, v96, s[4:5]
	v_add_f32_e32 v82, v28, v21
	v_cndmask_b32_e32 v29, -1.0, v1, vcc
	v_add_f32_e32 v6, v6, v12
	v_add_f32_e32 v7, v7, v13
	v_cndmask_b32_e64 v1, v96, v77, s[4:5]
	v_add_f32_e32 v1, v82, v1
	v_mov_b32_dpp v12, v6 quad_perm:[1,0,3,2] row_mask:0xf bank_mask:0xf bound_ctrl:1
	v_mov_b32_dpp v13, v7 quad_perm:[1,0,3,2] row_mask:0xf bank_mask:0xf bound_ctrl:1
	v_add_f32_dpp v1, v1, v1 quad_perm:[1,0,3,2] row_mask:0xf bank_mask:0xf bound_ctrl:1
	v_add_f32_e32 v6, v6, v12
	v_add_f32_e32 v7, v7, v13
	v_cmp_ge_i32_e32 vcc, s10, v236
	v_add_f32_dpp v1, v1, v1 quad_perm:[2,3,0,1] row_mask:0xf bank_mask:0xf bound_ctrl:1
	v_mov_b32_dpp v12, v6 quad_perm:[2,3,0,1] row_mask:0xf bank_mask:0xf bound_ctrl:1
	v_mov_b32_dpp v13, v7 quad_perm:[2,3,0,1] row_mask:0xf bank_mask:0xf bound_ctrl:1
	v_cndmask_b32_e32 v34, -1.0, v1, vcc
	v_add_f32_e32 v6, v6, v12
	v_add_f32_e32 v7, v7, v13
	v_cmp_ge_i32_e32 vcc, s10, v81
	v_or_b32_e32 v12, 26, v133
	ds_bpermute_b32 v16, v41, v15
	v_cndmask_b32_e32 v7, -1.0, v7, vcc
	v_cmp_ge_i32_e32 vcc, s10, v12
	ds_bpermute_b32 v18, v41, v4
	ds_bpermute_b32 v21, v41, v5
	v_cndmask_b32_e32 v6, -1.0, v6, vcc
	ds_bpermute_b32 v28, v41, v2
	ds_bpermute_b32 v42, v41, v3
	ds_bpermute_b32 v20, v41, v19
	ds_bpermute_b32 v23, v41, v8
	ds_bpermute_b32 v30, v41, v9
	ds_bpermute_b32 v26, v41, v10
	ds_bpermute_b32 v31, v41, v11
	ds_bpermute_b32 v25, v41, v24
	ds_bpermute_b32 v32, v41, v29
	ds_bpermute_b32 v125, v41, v34
	ds_bpermute_b32 v1, v41, v6
	ds_bpermute_b32 v126, v41, v7
	v_cmp_lt_i32_e32 vcc, 1, v214
	s_and_saveexec_b64 s[8:9], vcc
	s_xor_b64 s[8:9], exec, s[8:9]
	s_cbranch_execz .LBB0_503
	v_cmp_lt_i32_e32 vcc, 2, v214
	s_and_saveexec_b64 s[10:11], vcc
	s_xor_b64 s[10:11], exec, s[10:11]
	s_or_saveexec_b64 s[10:11], s[10:11]
	v_mov_b32_e32 v75, v34
	s_xor_b64 exec, exec, s[10:11]
	v_mov_b32_e32 v75, v11
	s_or_b64 exec, exec, s[10:11]
